# P1 weight-transpose load loops (w_d1, w_in) fully unrolled to 32 loads in flight, on top of P0 unroll and P3 epilogue
# baseline (speedup 1.0000x reference)
; __device__ __forceinline__ void transpose_item(const float* W, int K, int N, bf16_t* WT, int dst0, int src0, int mode, int nblk, LAS float* scr, int item, int lane) {
;     const int kb = item / nblk, nb = item % nblk, k0 = 64 * kb, n0 = 32 * nb;
;     const int sc = srccol(mode, n0 + (lane & 31), src0);
; #pragma unroll 8
;     for (int i = 0; i < 32; ++i) { const int kk = 2 * i + (lane >> 5); scr[kk * 33 + (lane & 31)] = __builtin_nontemporal_load(W + (size_t)(k0 + kk) * N + sc); }
.LBB0_66:
	v_add_u32_e32 v8, s13, v6
	v_ashrrev_i32_e32 v9, 31, v8
	v_add_u32_e32 v10, 2, v8
	v_add_u32_e32 v12, 4, v8
	v_add_u32_e32 v14, 6, v8
	v_add_u32_e32 v16, 8, v8
	v_add_u32_e32 v18, 10, v8
	v_add_u32_e32 v34, 12, v8
	v_add_u32_e32 v36, 14, v8
	v_lshlrev_b64 v[8:9], 13, v[8:9]
	v_ashrrev_i32_e32 v11, 31, v10
	v_ashrrev_i32_e32 v13, 31, v12
	v_ashrrev_i32_e32 v15, 31, v14
	v_ashrrev_i32_e32 v17, 31, v16
	v_ashrrev_i32_e32 v19, 31, v18
	v_ashrrev_i32_e32 v35, 31, v34
	v_ashrrev_i32_e32 v37, 31, v36
	v_lshl_add_u64 v[8:9], v[4:5], 0, v[8:9]
	v_lshlrev_b64 v[10:11], 13, v[10:11]
	v_lshlrev_b64 v[12:13], 13, v[12:13]
	v_lshlrev_b64 v[14:15], 13, v[14:15]
	v_lshlrev_b64 v[16:17], 13, v[16:17]
	v_lshlrev_b64 v[18:19], 13, v[18:19]
	v_lshlrev_b64 v[34:35], 13, v[34:35]
	v_lshlrev_b64 v[36:37], 13, v[36:37]
	v_lshl_add_u64 v[10:11], v[4:5], 0, v[10:11]
	v_lshl_add_u64 v[12:13], v[4:5], 0, v[12:13]
	v_lshl_add_u64 v[14:15], v[4:5], 0, v[14:15]
	v_lshl_add_u64 v[16:17], v[4:5], 0, v[16:17]
	v_lshl_add_u64 v[18:19], v[4:5], 0, v[18:19]
	v_lshl_add_u64 v[34:35], v[4:5], 0, v[34:35]
	v_lshl_add_u64 v[36:37], v[4:5], 0, v[36:37]
	global_load_dword v64, v[8:9], off nt
	global_load_dword v65, v[10:11], off nt
	global_load_dword v66, v[12:13], off nt
	global_load_dword v67, v[14:15], off nt
	global_load_dword v68, v[16:17], off nt
	global_load_dword v69, v[18:19], off nt
	global_load_dword v70, v[34:35], off nt
	global_load_dword v71, v[36:37], off nt
	s_add_i32 s13, s13, 16
	v_add_u32_e32 v8, s13, v6
	v_ashrrev_i32_e32 v9, 31, v8
	v_add_u32_e32 v10, 2, v8
	v_add_u32_e32 v12, 4, v8
	v_add_u32_e32 v14, 6, v8
	v_add_u32_e32 v16, 8, v8
	v_add_u32_e32 v18, 10, v8
	v_add_u32_e32 v34, 12, v8
	v_add_u32_e32 v36, 14, v8
	v_lshlrev_b64 v[8:9], 13, v[8:9]
	v_ashrrev_i32_e32 v11, 31, v10
	v_ashrrev_i32_e32 v13, 31, v12
	v_ashrrev_i32_e32 v15, 31, v14
	v_ashrrev_i32_e32 v17, 31, v16
	v_ashrrev_i32_e32 v19, 31, v18
	v_ashrrev_i32_e32 v35, 31, v34
	v_ashrrev_i32_e32 v37, 31, v36
	v_lshl_add_u64 v[8:9], v[4:5], 0, v[8:9]
	v_lshlrev_b64 v[10:11], 13, v[10:11]
	v_lshlrev_b64 v[12:13], 13, v[12:13]
	v_lshlrev_b64 v[14:15], 13, v[14:15]
	v_lshlrev_b64 v[16:17], 13, v[16:17]
	v_lshlrev_b64 v[18:19], 13, v[18:19]
	v_lshlrev_b64 v[34:35], 13, v[34:35]
	v_lshlrev_b64 v[36:37], 13, v[36:37]
	v_lshl_add_u64 v[10:11], v[4:5], 0, v[10:11]
	v_lshl_add_u64 v[12:13], v[4:5], 0, v[12:13]
	v_lshl_add_u64 v[14:15], v[4:5], 0, v[14:15]
	v_lshl_add_u64 v[16:17], v[4:5], 0, v[16:17]
	v_lshl_add_u64 v[18:19], v[4:5], 0, v[18:19]
	v_lshl_add_u64 v[34:35], v[4:5], 0, v[34:35]
	v_lshl_add_u64 v[36:37], v[4:5], 0, v[36:37]
	global_load_dword v72, v[8:9], off nt
	global_load_dword v73, v[10:11], off nt
	global_load_dword v74, v[12:13], off nt
	global_load_dword v75, v[14:15], off nt
	global_load_dword v76, v[16:17], off nt
	global_load_dword v77, v[18:19], off nt
	global_load_dword v78, v[34:35], off nt
	global_load_dword v79, v[36:37], off nt
	s_add_i32 s13, s13, 16
	v_add_u32_e32 v8, s13, v6
	v_ashrrev_i32_e32 v9, 31, v8
	v_add_u32_e32 v10, 2, v8
	v_add_u32_e32 v12, 4, v8
	v_add_u32_e32 v14, 6, v8
	v_add_u32_e32 v16, 8, v8
	v_add_u32_e32 v18, 10, v8
	v_add_u32_e32 v34, 12, v8
	v_add_u32_e32 v36, 14, v8
	v_lshlrev_b64 v[8:9], 13, v[8:9]
	v_ashrrev_i32_e32 v11, 31, v10
	v_ashrrev_i32_e32 v13, 31, v12
	v_ashrrev_i32_e32 v15, 31, v14
	v_ashrrev_i32_e32 v17, 31, v16
	v_ashrrev_i32_e32 v19, 31, v18
	v_ashrrev_i32_e32 v35, 31, v34
	v_ashrrev_i32_e32 v37, 31, v36
	v_lshl_add_u64 v[8:9], v[4:5], 0, v[8:9]
	v_lshlrev_b64 v[10:11], 13, v[10:11]
	v_lshlrev_b64 v[12:13], 13, v[12:13]
	v_lshlrev_b64 v[14:15], 13, v[14:15]
	v_lshlrev_b64 v[16:17], 13, v[16:17]
	v_lshlrev_b64 v[18:19], 13, v[18:19]
	v_lshlrev_b64 v[34:35], 13, v[34:35]
	v_lshlrev_b64 v[36:37], 13, v[36:37]
	v_lshl_add_u64 v[10:11], v[4:5], 0, v[10:11]
	v_lshl_add_u64 v[12:13], v[4:5], 0, v[12:13]
	v_lshl_add_u64 v[14:15], v[4:5], 0, v[14:15]
	v_lshl_add_u64 v[16:17], v[4:5], 0, v[16:17]
	v_lshl_add_u64 v[18:19], v[4:5], 0, v[18:19]
	v_lshl_add_u64 v[34:35], v[4:5], 0, v[34:35]
	v_lshl_add_u64 v[36:37], v[4:5], 0, v[36:37]
	global_load_dword v80, v[8:9], off nt
	global_load_dword v81, v[10:11], off nt
	global_load_dword v82, v[12:13], off nt
	global_load_dword v83, v[14:15], off nt
	global_load_dword v84, v[16:17], off nt
	global_load_dword v85, v[18:19], off nt
	global_load_dword v86, v[34:35], off nt
	global_load_dword v87, v[36:37], off nt
	s_add_i32 s13, s13, 16
	v_add_u32_e32 v8, s13, v6
	v_ashrrev_i32_e32 v9, 31, v8
	v_add_u32_e32 v10, 2, v8
	v_add_u32_e32 v12, 4, v8
	v_add_u32_e32 v14, 6, v8
	v_add_u32_e32 v16, 8, v8
	v_add_u32_e32 v18, 10, v8
	v_add_u32_e32 v34, 12, v8
	v_add_u32_e32 v36, 14, v8
	v_lshlrev_b64 v[8:9], 13, v[8:9]
	v_ashrrev_i32_e32 v11, 31, v10
	v_ashrrev_i32_e32 v13, 31, v12
	v_ashrrev_i32_e32 v15, 31, v14
	v_ashrrev_i32_e32 v17, 31, v16
	v_ashrrev_i32_e32 v19, 31, v18
	v_ashrrev_i32_e32 v35, 31, v34
	v_ashrrev_i32_e32 v37, 31, v36
	v_lshl_add_u64 v[8:9], v[4:5], 0, v[8:9]
	v_lshlrev_b64 v[10:11], 13, v[10:11]
	v_lshlrev_b64 v[12:13], 13, v[12:13]
	v_lshlrev_b64 v[14:15], 13, v[14:15]
	v_lshlrev_b64 v[16:17], 13, v[16:17]
	v_lshlrev_b64 v[18:19], 13, v[18:19]
	v_lshlrev_b64 v[34:35], 13, v[34:35]
	v_lshlrev_b64 v[36:37], 13, v[36:37]
	v_lshl_add_u64 v[10:11], v[4:5], 0, v[10:11]
	v_lshl_add_u64 v[12:13], v[4:5], 0, v[12:13]
	v_lshl_add_u64 v[14:15], v[4:5], 0, v[14:15]
	v_lshl_add_u64 v[16:17], v[4:5], 0, v[16:17]
	v_lshl_add_u64 v[18:19], v[4:5], 0, v[18:19]
	v_lshl_add_u64 v[34:35], v[4:5], 0, v[34:35]
	v_lshl_add_u64 v[36:37], v[4:5], 0, v[36:37]
	global_load_dword v88, v[8:9], off nt
	global_load_dword v89, v[10:11], off nt
	global_load_dword v90, v[12:13], off nt
	global_load_dword v91, v[14:15], off nt
	global_load_dword v92, v[16:17], off nt
	global_load_dword v93, v[18:19], off nt
	global_load_dword v94, v[34:35], off nt
	global_load_dword v95, v[36:37], off nt
	s_add_i32 s13, s13, 16
	v_add_u32_e32 v8, 0x400, v7
	s_waitcnt vmcnt(30)
; #define LAS __attribute__((address_space(3)))
; __device__ __forceinline__ unsigned pk2(float lo, float hi) { return pg8::cvt_pk_bf16(lo, hi); }
; __device__ __forceinline__ void transpose_item(const float* W, int K, int N, bf16_t* WT, int dst0, int src0, int mode, int nblk, LAS float* scr, int item, int lane) {
;     ...
;     for (int i = 0; i < 32; ++i) { const int kk = 2 * i + (lane >> 5); scr[kk * 33 + (lane & 31)] = __builtin_nontemporal_load(W + (size_t)(k0 + kk) * N + sc); }
;     asm volatile("s_waitcnt lgkmcnt(0)" ::: "memory");
;     const int c = lane & 7;
; #pragma unroll
;     for (int j = 0; j < 4; ++j) { const int n = (lane >> 3) + 8 * j; const LAS float* s = scr + (8 * c) * 33 + n;
;         u32x4 o; o.x = pk2(s[0 * 33], s[1 * 33]); o.y = pk2(s[2 * 33], s[3 * 33]); o.z = pk2(s[4 * 33], s[5 * 33]); o.w = pk2(s[6 * 33], s[7 * 33]);
;         *(u32x4*)(WT + (size_t)(dst0 + n0 + n) * K + k0 + 8 * c) = o; }
;     asm volatile("s_waitcnt lgkmcnt(0)" ::: "memory");
	ds_write2_b32 v7, v64, v65 offset1:66
	s_waitcnt vmcnt(28)
	ds_write2_b32 v7, v66, v67 offset0:132 offset1:198
	s_waitcnt vmcnt(26)
	ds_write2_b32 v8, v68, v69 offset0:8 offset1:74
	s_waitcnt vmcnt(24)
	ds_write2_b32 v8, v70, v71 offset0:140 offset1:206
	v_add_u32_e32 v7, 0x840, v7
	v_add_u32_e32 v8, 0x400, v7
	s_waitcnt vmcnt(22)
	ds_write2_b32 v7, v72, v73 offset1:66
	s_waitcnt vmcnt(20)
	ds_write2_b32 v7, v74, v75 offset0:132 offset1:198
	s_waitcnt vmcnt(18)
	ds_write2_b32 v8, v76, v77 offset0:8 offset1:74
	s_waitcnt vmcnt(16)
	ds_write2_b32 v8, v78, v79 offset0:140 offset1:206
	v_add_u32_e32 v7, 0x840, v7
	v_add_u32_e32 v8, 0x400, v7
	s_waitcnt vmcnt(14)
	ds_write2_b32 v7, v80, v81 offset1:66
	s_waitcnt vmcnt(12)
	ds_write2_b32 v7, v82, v83 offset0:132 offset1:198
	s_waitcnt vmcnt(10)
	ds_write2_b32 v8, v84, v85 offset0:8 offset1:74
	s_waitcnt vmcnt(8)
	ds_write2_b32 v8, v86, v87 offset0:140 offset1:206
	v_add_u32_e32 v7, 0x840, v7
	v_add_u32_e32 v8, 0x400, v7
	s_waitcnt vmcnt(6)
	ds_write2_b32 v7, v88, v89 offset1:66
	s_waitcnt vmcnt(4)
	ds_write2_b32 v7, v90, v91 offset0:132 offset1:198
	s_waitcnt vmcnt(2)
	ds_write2_b32 v8, v92, v93 offset0:8 offset1:74
	s_waitcnt vmcnt(0)
	ds_write2_b32 v8, v94, v95 offset0:140 offset1:206
	v_add_u32_e32 v7, 0x840, v7
	s_cmp_lg_u32 s13, 64
	s_waitcnt lgkmcnt(0)
	ds_read2_b32 v[8:9], v22 offset0:33 offset1:41
	ds_read2_b32 v[10:11], v22 offset1:8
	ds_read2_b32 v[12:13], v22 offset0:66 offset1:74
	ds_read2_b32 v[14:15], v22 offset0:99 offset1:107
	ds_read2_b32 v[16:17], v22 offset0:132 offset1:140
	ds_read2_b32 v[18:19], v22 offset0:165 offset1:173
	ds_read2_b32 v[34:35], v22 offset0:198 offset1:206
	ds_read2_b32 v[36:37], v22 offset0:231 offset1:239
	s_waitcnt lgkmcnt(6)
	v_cvt_pk_bf16_f32 v4, v10, v8
	v_or_b32_e32 v8, s19, v157
	s_ashr_i32 s13, s12, 31
	v_mul_lo_u32 v40, v8, s14
	v_lshl_add_u64 v[38:39], s[12:13], 1, v[0:1]
	v_ashrrev_i32_e32 v41, 31, v40
	s_waitcnt lgkmcnt(4)
	v_cvt_pk_bf16_f32 v5, v12, v14
	s_waitcnt lgkmcnt(2)
	v_cvt_pk_bf16_f32 v6, v16, v18
	s_waitcnt lgkmcnt(0)
	v_cvt_pk_bf16_f32 v7, v34, v36
	v_lshl_add_u64 v[40:41], v[40:41], 1, v[38:39]
	v_or_b32_e32 v8, s19, v23
	global_store_dwordx4 v[40:41], v[4:7], off
	v_mul_lo_u32 v8, v8, s14
	s_nop 0
	v_cvt_pk_bf16_f32 v4, v11, v9
	v_cvt_pk_bf16_f32 v5, v13, v15
	v_cvt_pk_bf16_f32 v6, v17, v19
	v_cvt_pk_bf16_f32 v7, v35, v37
	v_ashrrev_i32_e32 v9, 31, v8
	ds_read2_b32 v[10:11], v22 offset0:49 offset1:57
	ds_read2_b32 v[12:13], v22 offset0:16 offset1:24
	ds_read2_b32 v[14:15], v22 offset0:82 offset1:90
	ds_read2_b32 v[16:17], v22 offset0:115 offset1:123
	ds_read2_b32 v[18:19], v22 offset0:148 offset1:156
	ds_read2_b32 v[34:35], v22 offset0:181 offset1:189
	ds_read2_b32 v[36:37], v22 offset0:214 offset1:222
	ds_read2_b32 v[40:41], v22 offset0:247 offset1:255
	v_lshl_add_u64 v[8:9], v[8:9], 1, v[38:39]
	global_store_dwordx4 v[8:9], v[4:7], off
	v_or_b32_e32 v8, s19, v24
	v_mul_lo_u32 v8, v8, s14
	v_ashrrev_i32_e32 v9, 31, v8
	s_waitcnt lgkmcnt(6)
	v_cvt_pk_bf16_f32 v4, v12, v10
	s_waitcnt lgkmcnt(4)
	v_cvt_pk_bf16_f32 v5, v14, v16
	s_waitcnt lgkmcnt(2)
	v_cvt_pk_bf16_f32 v6, v18, v34
	s_waitcnt lgkmcnt(0)
	v_cvt_pk_bf16_f32 v7, v36, v40
	v_lshl_add_u64 v[8:9], v[8:9], 1, v[38:39]
	global_store_dwordx4 v[8:9], v[4:7], off
	v_or_b32_e32 v8, s19, v25
	v_mul_lo_u32 v8, v8, s14
	v_ashrrev_i32_e32 v9, 31, v8
	v_cvt_pk_bf16_f32 v4, v13, v11
	v_cvt_pk_bf16_f32 v5, v15, v17
	v_cvt_pk_bf16_f32 v6, v19, v35
	v_cvt_pk_bf16_f32 v7, v37, v41
	v_lshl_add_u64 v[8:9], v[8:9], 1, v[38:39]
	global_store_dwordx4 v[8:9], v[4:7], off
	s_waitcnt lgkmcnt(0)
	s_mov_b32 s19, s18
	s_andn2_b64 vcc, exec, s[10:11]
	s_cbranch_vccnz .LBB0_60

; #define LAS __attribute__((address_space(3)))
; __device__ __forceinline__ unsigned pk2(float lo, float hi) { return pg8::cvt_pk_bf16(lo, hi); }
; __device__ __forceinline__ void transpose_item(const float* W, int K, int N, bf16_t* WT, int dst0, int src0, int mode, int nblk, LAS float* scr, int item, int lane) {
;     ...
;     const int sc = srccol(mode, n0 + (lane & 31), src0);
; #pragma unroll 8
;     for (int i = 0; i < 32; ++i) { const int kk = 2 * i + (lane >> 5); scr[kk * 33 + (lane & 31)] = __builtin_nontemporal_load(W + (size_t)(k0 + kk) * N + sc); }
;     asm volatile("s_waitcnt lgkmcnt(0)" ::: "memory");
;     const int c = lane & 7;
; #pragma unroll
;     for (int j = 0; j < 4; ++j) { const int n = (lane >> 3) + 8 * j; const LAS float* s = scr + (8 * c) * 33 + n;
;         u32x4 o; o.x = pk2(s[0 * 33], s[1 * 33]); o.y = pk2(s[2 * 33], s[3 * 33]); o.z = pk2(s[4 * 33], s[5 * 33]); o.w = pk2(s[6 * 33], s[7 * 33]);
;         *(u32x4*)(WT + (size_t)(dst0 + n0 + n) * K + k0 + 8 * c) = o; }
;     asm volatile("s_waitcnt lgkmcnt(0)" ::: "memory");
.LBB0_69:
	v_lshl_add_u64 v[36:37], v[18:19], 0, s[12:13]
	v_lshl_add_u64 v[38:39], v[16:17], 0, s[12:13]
	v_lshl_add_u64 v[40:41], v[14:15], 0, s[12:13]
	v_lshl_add_u64 v[42:43], v[12:13], 0, s[12:13]
	v_lshl_add_u64 v[44:45], v[10:11], 0, s[12:13]
	v_lshl_add_u64 v[46:47], v[8:9], 0, s[12:13]
	v_lshl_add_u64 v[48:49], v[6:7], 0, s[12:13]
	v_lshl_add_u64 v[50:51], v[4:5], 0, s[12:13]
	global_load_dword v64, v[36:37], off nt
	global_load_dword v65, v[38:39], off nt
	global_load_dword v66, v[40:41], off nt
	global_load_dword v67, v[42:43], off nt
	global_load_dword v68, v[44:45], off nt
	global_load_dword v69, v[46:47], off nt
	global_load_dword v70, v[48:49], off nt
	global_load_dword v71, v[50:51], off nt
	s_add_u32 s12, s12, 0x130400
	s_addc_u32 s13, s13, 0
	v_lshl_add_u64 v[36:37], v[18:19], 0, s[12:13]
	v_lshl_add_u64 v[38:39], v[16:17], 0, s[12:13]
	v_lshl_add_u64 v[40:41], v[14:15], 0, s[12:13]
	v_lshl_add_u64 v[42:43], v[12:13], 0, s[12:13]
	v_lshl_add_u64 v[44:45], v[10:11], 0, s[12:13]
	v_lshl_add_u64 v[46:47], v[8:9], 0, s[12:13]
	v_lshl_add_u64 v[48:49], v[6:7], 0, s[12:13]
	v_lshl_add_u64 v[50:51], v[4:5], 0, s[12:13]
	global_load_dword v72, v[36:37], off nt
	global_load_dword v73, v[38:39], off nt
	global_load_dword v74, v[40:41], off nt
	global_load_dword v75, v[42:43], off nt
	global_load_dword v76, v[44:45], off nt
	global_load_dword v77, v[46:47], off nt
	global_load_dword v78, v[48:49], off nt
	global_load_dword v79, v[50:51], off nt
	s_add_u32 s12, s12, 0x130400
	s_addc_u32 s13, s13, 0
	v_lshl_add_u64 v[36:37], v[18:19], 0, s[12:13]
	v_lshl_add_u64 v[38:39], v[16:17], 0, s[12:13]
	v_lshl_add_u64 v[40:41], v[14:15], 0, s[12:13]
	v_lshl_add_u64 v[42:43], v[12:13], 0, s[12:13]
	v_lshl_add_u64 v[44:45], v[10:11], 0, s[12:13]
	v_lshl_add_u64 v[46:47], v[8:9], 0, s[12:13]
	v_lshl_add_u64 v[48:49], v[6:7], 0, s[12:13]
	v_lshl_add_u64 v[50:51], v[4:5], 0, s[12:13]
	global_load_dword v80, v[36:37], off nt
	global_load_dword v81, v[38:39], off nt
	global_load_dword v82, v[40:41], off nt
	global_load_dword v83, v[42:43], off nt
	global_load_dword v84, v[44:45], off nt
	global_load_dword v85, v[46:47], off nt
	global_load_dword v86, v[48:49], off nt
	global_load_dword v87, v[50:51], off nt
	s_add_u32 s12, s12, 0x130400
	s_addc_u32 s13, s13, 0
	v_lshl_add_u64 v[36:37], v[18:19], 0, s[12:13]
	v_lshl_add_u64 v[38:39], v[16:17], 0, s[12:13]
	v_lshl_add_u64 v[40:41], v[14:15], 0, s[12:13]
	v_lshl_add_u64 v[42:43], v[12:13], 0, s[12:13]
	v_lshl_add_u64 v[44:45], v[10:11], 0, s[12:13]
	v_lshl_add_u64 v[46:47], v[8:9], 0, s[12:13]
	v_lshl_add_u64 v[48:49], v[6:7], 0, s[12:13]
	v_lshl_add_u64 v[50:51], v[4:5], 0, s[12:13]
	global_load_dword v88, v[36:37], off nt
	global_load_dword v89, v[38:39], off nt
	global_load_dword v90, v[40:41], off nt
	global_load_dword v91, v[42:43], off nt
	global_load_dword v92, v[44:45], off nt
	global_load_dword v93, v[46:47], off nt
	global_load_dword v94, v[48:49], off nt
	global_load_dword v95, v[50:51], off nt
	s_add_u32 s12, s12, 0x130400
	s_addc_u32 s13, s13, 0
	v_add_u32_e32 v36, 0x400, v34
	s_waitcnt vmcnt(30)
	ds_write2_b32 v34, v64, v65 offset1:66
	s_waitcnt vmcnt(28)
	ds_write2_b32 v34, v66, v67 offset0:132 offset1:198
	s_waitcnt vmcnt(26)
	ds_write2_b32 v36, v68, v69 offset0:8 offset1:74
	s_waitcnt vmcnt(24)
	ds_write2_b32 v36, v70, v71 offset0:140 offset1:206
	v_add_u32_e32 v34, 0x840, v34
	v_add_u32_e32 v36, 0x400, v34
	s_waitcnt vmcnt(22)
	ds_write2_b32 v34, v72, v73 offset1:66
	s_waitcnt vmcnt(20)
	ds_write2_b32 v34, v74, v75 offset0:132 offset1:198
	s_waitcnt vmcnt(18)
	ds_write2_b32 v36, v76, v77 offset0:8 offset1:74
	s_waitcnt vmcnt(16)
	ds_write2_b32 v36, v78, v79 offset0:140 offset1:206
	v_add_u32_e32 v34, 0x840, v34
	v_add_u32_e32 v36, 0x400, v34
	s_waitcnt vmcnt(14)
	ds_write2_b32 v34, v80, v81 offset1:66
	s_waitcnt vmcnt(12)
	ds_write2_b32 v34, v82, v83 offset0:132 offset1:198
	s_waitcnt vmcnt(10)
	ds_write2_b32 v36, v84, v85 offset0:8 offset1:74
	s_waitcnt vmcnt(8)
	ds_write2_b32 v36, v86, v87 offset0:140 offset1:206
	v_add_u32_e32 v34, 0x840, v34
	v_add_u32_e32 v36, 0x400, v34
	s_waitcnt vmcnt(6)
	ds_write2_b32 v34, v88, v89 offset1:66
	s_waitcnt vmcnt(4)
	ds_write2_b32 v34, v90, v91 offset0:132 offset1:198
	s_waitcnt vmcnt(2)
	ds_write2_b32 v36, v92, v93 offset0:8 offset1:74
	s_waitcnt vmcnt(0)
	ds_write2_b32 v36, v94, v95 offset0:140 offset1:206
	v_add_u32_e32 v34, 0x840, v34
	s_cmp_lg_u32 s12, 0x4c1000
	s_waitcnt lgkmcnt(0)
	ds_read2_b32 v[8:9], v22 offset0:33 offset1:41
	ds_read2_b32 v[10:11], v22 offset1:8
	ds_read2_b32 v[12:13], v22 offset0:66 offset1:74
	ds_read2_b32 v[14:15], v22 offset0:99 offset1:107
	ds_read2_b32 v[16:17], v22 offset0:132 offset1:140
	ds_read2_b32 v[18:19], v22 offset0:165 offset1:173
	ds_read2_b32 v[34:35], v22 offset0:198 offset1:206
	ds_read2_b32 v[36:37], v22 offset0:231 offset1:239
	v_or_b32_e32 v40, s19, v157
	s_ashr_i32 s11, s10, 31
	v_ashrrev_i32_e32 v41, 31, v40
	v_lshl_add_u64 v[38:39], s[10:11], 1, v[2:3]
	v_lshlrev_b64 v[40:41], 12, v[40:41]
	s_waitcnt lgkmcnt(6)
	v_cvt_pk_bf16_f32 v4, v10, v8
	s_waitcnt lgkmcnt(4)
	v_cvt_pk_bf16_f32 v5, v12, v14
	s_waitcnt lgkmcnt(2)
	v_cvt_pk_bf16_f32 v6, v16, v18
	s_waitcnt lgkmcnt(0)
	v_cvt_pk_bf16_f32 v7, v34, v36
	v_lshl_add_u64 v[40:41], v[38:39], 0, v[40:41]
	v_or_b32_e32 v8, s19, v23
	global_store_dwordx4 v[40:41], v[4:7], off
	s_nop 1
	v_cvt_pk_bf16_f32 v4, v11, v9
	v_ashrrev_i32_e32 v9, 31, v8
	v_cvt_pk_bf16_f32 v5, v13, v15
	v_cvt_pk_bf16_f32 v6, v17, v19
	v_cvt_pk_bf16_f32 v7, v35, v37
	v_lshlrev_b64 v[8:9], 12, v[8:9]
	ds_read2_b32 v[10:11], v22 offset0:49 offset1:57
	ds_read2_b32 v[12:13], v22 offset0:16 offset1:24
	ds_read2_b32 v[14:15], v22 offset0:82 offset1:90
	ds_read2_b32 v[16:17], v22 offset0:115 offset1:123
	ds_read2_b32 v[18:19], v22 offset0:148 offset1:156
	ds_read2_b32 v[34:35], v22 offset0:181 offset1:189
	ds_read2_b32 v[36:37], v22 offset0:214 offset1:222
	ds_read2_b32 v[40:41], v22 offset0:247 offset1:255
	v_lshl_add_u64 v[8:9], v[38:39], 0, v[8:9]
	global_store_dwordx4 v[8:9], v[4:7], off
	v_or_b32_e32 v8, s19, v24
	v_ashrrev_i32_e32 v9, 31, v8
	v_lshlrev_b64 v[8:9], 12, v[8:9]
	s_waitcnt lgkmcnt(6)
	v_cvt_pk_bf16_f32 v4, v12, v10
	s_waitcnt lgkmcnt(4)
	v_cvt_pk_bf16_f32 v5, v14, v16
	s_waitcnt lgkmcnt(2)
	v_cvt_pk_bf16_f32 v6, v18, v34
	s_waitcnt lgkmcnt(0)
	v_cvt_pk_bf16_f32 v7, v36, v40
	v_lshl_add_u64 v[8:9], v[38:39], 0, v[8:9]
	global_store_dwordx4 v[8:9], v[4:7], off
	v_or_b32_e32 v8, s19, v25
	v_ashrrev_i32_e32 v9, 31, v8
	v_lshlrev_b64 v[8:9], 12, v[8:9]
	v_cvt_pk_bf16_f32 v4, v13, v11
	v_cvt_pk_bf16_f32 v5, v15, v17
	v_cvt_pk_bf16_f32 v6, v19, v35
	v_cvt_pk_bf16_f32 v7, v37, v41
	v_lshl_add_u64 v[8:9], v[38:39], 0, v[8:9]
	global_store_dwordx4 v[8:9], v[4:7], off
	s_waitcnt lgkmcnt(0)
	s_branch .LBB0_60
